# phase 19 pair loop: LDS-DMA addresses as SGPR base plus precomputed 32-bit lane offsets (no 64-bit VALU adds in the loop)
# baseline (speedup 1.0000x reference)
; #define ATT_ISSUE2(p_, st_) do { LAS unsigned char* sp_ = lds + (st_) * STG2; const int ta_ = dual ? (p_) : 2 * (p_), tb_ = dual ? (p_) : 2 * (p_) + 1; ATT_ISSUE1(u, ta_, sp_); ATT_ISSUEM(ta_, sp_ + 2 * STAGEB); \
;         if (dual || tb_ < u.ntiles) { ATT_ISSUE1(ub, tb_, sp_ + STAGEB); ATT_ISSUEM(tb_, sp_ + 2 * STAGEB + MSKB); } } while (0)
;     ...
;         const AttnUnit& ub = dual ? u2 : u;
;         const int npairs = dual ? u.ntiles : (u.ntiles + 1) >> 1, p0 = dual ? T0 : T0 >> 1;
;         ATT_ISSUE2(p0, p0 & 1);
.LBB0_3293:
	v_and_b32_e32 v186, 63, v3
	v_lshrrev_b32_e32 v5, 4, v186
	v_or_b32_e32 v162, s54, v5
	v_bitop3_b32 v9, v5, v3, s54 bitop3:0x36
	v_lshlrev_b64 v[174:175], 12, v[162:163]
	v_lshlrev_b32_e32 v9, 4, v9
	v_and_b32_e32 v4, 15, v3
	v_lshlrev_b32_e32 v8, 2, v5
	v_lshl_add_u64 v[6:7], s[30:31], 0, v[174:175]
	v_and_b32_e32 v162, 0xf0, v9
	s_mov_b32 m0, s68
	v_lshl_add_u64 v[6:7], v[6:7], 0, v[162:163]
	v_bitop3_b32 v9, v8, v4, s65 bitop3:0x36
	global_load_lds_dwordx4 v[6:7], off
	v_lshl_add_u64 v[6:7], s[4:5], 0, v[174:175]
	v_lshlrev_b32_e32 v176, 4, v9
	v_mov_b32_e32 v177, v163
	v_lshl_add_u64 v[6:7], v[6:7], 0, v[176:177]
	s_add_i32 m0, s68, 0x4000
	v_mov_b32_e32 v181, v163
	global_load_lds_dwordx4 v[6:7], off
	v_or_b32_e32 v6, s55, v5
	v_mov_b32_e32 v7, v163
	v_bitop3_b32 v5, v5, v3, s55 bitop3:0x36
	v_lshlrev_b64 v[178:179], 12, v[6:7]
	v_lshlrev_b32_e32 v5, 4, v5
	v_lshl_add_u64 v[6:7], s[30:31], 0, v[178:179]
	v_and_b32_e32 v180, 0xf0, v5
	s_add_i32 s6, s66, 0
	v_lshl_add_u64 v[6:7], v[6:7], 0, v[180:181]
	s_mov_b32 m0, s6
	v_bitop3_b32 v5, v8, v4, s67 bitop3:0x36
	global_load_lds_dwordx4 v[6:7], off
	v_lshl_add_u64 v[6:7], s[4:5], 0, v[178:179]
	v_lshlrev_b32_e32 v182, 4, v5
	v_mov_b32_e32 v183, v163
	v_lshl_add_u64 v[6:7], v[6:7], 0, v[182:183]
	s_add_i32 m0, s6, 0x4000
	s_lshl_b32 s44, s97, 1
	global_load_lds_dwordx4 v[6:7], off
	v_add_u32_e32 v248, v174, v162
	v_add_u32_e32 v249, v174, v176
	v_add_u32_e32 v250, v178, v180
	v_add_u32_e32 v251, v178, v182
	s_or_b32 s21, s44, 1
	s_cmp_ge_u32 s21, s89
	s_cselect_b64 s[4:5], -1, 0
	s_and_b64 s[4:5], s[24:25], s[4:5]
	s_and_b64 vcc, exec, s[4:5]
	s_cbranch_vccnz .LBB0_3299
	s_mov_b64 s[34:35], -1
	s_and_b64 vcc, exec, s[26:27]
	s_cbranch_vccz .LBB0_3296
	s_ashr_i32 s3, s2, 31
	s_lshl_b64 s[30:31], s[2:3], 24
	s_lshl_b32 s3, s36, 8
	s_lshl_b32 s4, s39, 18
	s_or_b32 s3, s4, s3
	s_or_b32 s3, s30, s3
	s_add_u32 s4, s62, s3
	s_addc_u32 s5, s63, s31
	s_add_u32 s30, s70, s3
	s_addc_u32 s31, s71, s31
	s_mov_b64 s[34:35], 0

.LBB0_3308:
	s_bitcmp1_b32 s96, 0
	s_cselect_b32 s45, 0x10400, 0
	s_add_i32 s61, s45, 0
	s_add_i32 s60, s61, s64
	s_mov_b32 m0, s60
	s_add_i32 s61, s61, s66
	global_load_lds_dwordx4 v248, s[2:3]
	s_add_i32 m0, s60, 0x4000
	s_nop 0
	global_load_lds_dwordx4 v249, s[4:5]
	s_mov_b32 m0, s61
	s_nop 0
	global_load_lds_dwordx4 v250, s[2:3]
	s_add_i32 s2, s94, 2
	s_add_i32 m0, s61, 0x4000
	s_cmp_ge_i32 s2, s89
	global_load_lds_dwordx4 v251, s[4:5]
	s_cselect_b64 s[2:3], -1, 0
	s_and_b64 s[2:3], s[24:25], s[2:3]
	s_and_b64 vcc, exec, s[2:3]
	s_cbranch_vccnz .LBB0_3316
	s_mov_b64 s[48:49], -1
	s_and_b64 vcc, exec, s[26:27]
	s_cbranch_vccz .LBB0_3313
	s_cmp_gt_u32 s97, 62
	s_mov_b64 s[4:5], s[42:43]
	s_mov_b64 s[2:3], s[40:41]
	s_cbranch_scc1 .LBB0_3312
	s_add_u32 s2, s92, s95
	s_addc_u32 s3, s93, 0
	s_lshl_b64 s[4:5], s[2:3], 8
	s_add_u32 s2, s62, s4
	s_addc_u32 s3, s63, s5
	s_add_u32 s4, s70, s4
	s_addc_u32 s5, s71, s5

.LBB0_3315:
	s_add_i32 m0, s60, 0x8000
	s_nop 0
	global_load_lds_dwordx4 v248, s[2:3]
	s_add_i32 m0, s60, 0xc000
	s_nop 0
	global_load_lds_dwordx4 v249, s[4:5]
	s_add_i32 m0, s61, 0x8000
	s_nop 0
	global_load_lds_dwordx4 v250, s[2:3]
	s_add_i32 m0, s61, 0xc000
	s_nop 0
	global_load_lds_dwordx4 v251, s[4:5]
